# grid barrier: first-arriving workgroup of each XCD starts an early L2 write-back while it waits
# speedup vs baseline: 1.0015x; 1.0015x over previous
; __device__ __forceinline__ unsigned xb_ld(unsigned* p)              { return __hip_atomic_load(p, __ATOMIC_RELAXED, __HIP_MEMORY_SCOPE_AGENT); }
; __device__ __forceinline__ unsigned xb_add(unsigned* p, unsigned v) { return __hip_atomic_fetch_add(p, v, __ATOMIC_RELAXED, __HIP_MEMORY_SCOPE_AGENT); }
; #define XB_SPIN(cond, bar) do { unsigned _sp = 0; while (cond) { __builtin_amdgcn_s_sleep(1); \
;     if ((++_sp & 255u) == 0u) { if (xb_ld(&(bar)[XB_TMO])) break; if (_sp > XB_SPIN_CAP) { atomicAdd(&(bar)[XB_TMO], 1u); break; } } } } while (0)
; __device__ __forceinline__ void xcd_barrier(unsigned* bar, volatile LAS unsigned* st) {
;     ...
;     const unsigned old = xb_add(&bar[XB_XSUB(x)], 1u);
;     const unsigned gen = old / nloc;
;     if (old + 1u == (gen + 1u) * nloc) {
;       __builtin_amdgcn_fence(__ATOMIC_RELEASE, "agent");
;       asm volatile("s_waitcnt vmcnt(0)" ::: "memory");
;       const unsigned og = xb_add(&bar[XB_TOP], 1u);
;       const unsigned tg = og / nx;
;       if (og + 1u == (tg + 1u) * nx) xb_add(&bar[XB_TOPGEN], 1u);
;       else XB_SPIN(xb_ld(&bar[XB_TOPGEN]) == tg, bar);
;       __builtin_amdgcn_fence(__ATOMIC_ACQUIRE, "agent");
;       xb_add(&bar[XB_XGEN(x)], 1u);
;       asm volatile("s_waitcnt vmcnt(0)" ::: "memory");
;     } else {
;       XB_SPIN(xb_ld(&bar[XB_XGEN(x)]) == gen, bar);
.LBB0_177:
	s_or_b64 exec, exec, s[2:3]
	v_cvt_f32_u32_e32 v4, v2
	s_waitcnt vmcnt(0)
	v_readfirstlane_b32 s0, v3
	v_sub_u32_e32 v3, 0, v2
	v_rcp_iflag_f32_e32 v4, v4
	v_add_u32_e32 v5, s0, v1
	v_mul_f32_e32 v4, 0x4f7ffffe, v4
	v_cvt_u32_f32_e32 v4, v4
	v_mul_lo_u32 v1, v3, v4
	v_mul_hi_u32 v1, v4, v1
	v_add_u32_e32 v1, v4, v1
	v_mul_hi_u32 v1, v5, v1
	v_mul_lo_u32 v3, v1, v2
	v_sub_u32_e32 v3, v5, v3
	v_add_u32_e32 v4, 1, v1
	v_cmp_ge_u32_e32 vcc, v3, v2
	s_nop 1
	v_cndmask_b32_e32 v1, v1, v4, vcc
	v_sub_u32_e32 v4, v3, v2
	v_cndmask_b32_e32 v3, v3, v4, vcc
	v_add_u32_e32 v4, 1, v1
	v_cmp_ge_u32_e32 vcc, v3, v2
	v_add_u32_e32 v3, 1, v5
	s_nop 0
	v_cndmask_b32_e32 v1, v1, v4, vcc
	v_mul_lo_u32 v4, v2, v1
	v_add_u32_e32 v2, v4, v2
	v_cmp_ne_u32_e32 vcc, v3, v2
	s_and_saveexec_b64 s[0:1], vcc
	s_xor_b64 s[0:1], exec, s[0:1]
	s_cbranch_execz .LBB0_191
	v_cmp_eq_u32_e32 vcc, v5, v4
	s_cbranch_vccz .Lbar6_1
	buffer_wbl2 sc1
.Lbar6_1:
	v_mov_b32_e32 v0, 0x3000
	global_load_dword v0, v0, s[8:9] offset:1280 sc1
	s_add_u32 s4, s8, 0x3500
	s_addc_u32 s5, s9, 0
	s_waitcnt vmcnt(0)
	v_cmp_eq_u32_e32 vcc, v0, v1
	s_and_saveexec_b64 s[2:3], vcc
	s_cbranch_execz .LBB0_190
	s_mov_b32 s22, 1
	s_mov_b64 s[12:13], 0
	v_mov_b32_e32 v0, 0
	s_branch .LBB0_181

; __device__ __forceinline__ unsigned xb_ld(unsigned* p)              { return __hip_atomic_load(p, __ATOMIC_RELAXED, __HIP_MEMORY_SCOPE_AGENT); }
; __device__ __forceinline__ unsigned xb_add(unsigned* p, unsigned v) { return __hip_atomic_fetch_add(p, v, __ATOMIC_RELAXED, __HIP_MEMORY_SCOPE_AGENT); }
; #define XB_SPIN(cond, bar) do { unsigned _sp = 0; while (cond) { __builtin_amdgcn_s_sleep(1); \
;     if ((++_sp & 255u) == 0u) { if (xb_ld(&(bar)[XB_TMO])) break; if (_sp > XB_SPIN_CAP) { atomicAdd(&(bar)[XB_TMO], 1u); break; } } } } while (0)
; __device__ __forceinline__ void xcd_barrier(unsigned* bar, volatile LAS unsigned* st) {
;     ...
;       const unsigned og = xb_add(&bar[XB_TOP], 1u);
;       const unsigned tg = og / nx;
;       if (og + 1u == (tg + 1u) * nx) xb_add(&bar[XB_TOPGEN], 1u);
;       else XB_SPIN(xb_ld(&bar[XB_TOPGEN]) == tg, bar);
;       __builtin_amdgcn_fence(__ATOMIC_ACQUIRE, "agent");
;       xb_add(&bar[XB_XGEN(x)], 1u);
;       asm volatile("s_waitcnt vmcnt(0)" ::: "memory");
;     } else {
;       XB_SPIN(xb_ld(&bar[XB_XGEN(x)]) == gen, bar);
.Lbar6_2:
	v_mov_b32_e32 v0, 0x3000
	global_load_dword v0, v0, s[10:11] offset:1280 sc1
	s_add_u32 s4, s10, 0x3500
	s_addc_u32 s5, s11, 0
	s_waitcnt vmcnt(0)
	v_cmp_eq_u32_e32 vcc, v0, v1
	s_and_saveexec_b64 s[2:3], vcc
	s_cbranch_execz .LBB0_258
	s_mov_b32 s22, 1
	s_mov_b64 s[12:13], 0
	v_mov_b32_e32 v0, 0
	s_branch .LBB0_249

; __device__ __forceinline__ unsigned xb_ld(unsigned* p)              { return __hip_atomic_load(p, __ATOMIC_RELAXED, __HIP_MEMORY_SCOPE_AGENT); }
; __device__ __forceinline__ unsigned xb_add(unsigned* p, unsigned v) { return __hip_atomic_fetch_add(p, v, __ATOMIC_RELAXED, __HIP_MEMORY_SCOPE_AGENT); }
; #define XB_SPIN(cond, bar) do { unsigned _sp = 0; while (cond) { __builtin_amdgcn_s_sleep(1); \
;     if ((++_sp & 255u) == 0u) { if (xb_ld(&(bar)[XB_TMO])) break; if (_sp > XB_SPIN_CAP) { atomicAdd(&(bar)[XB_TMO], 1u); break; } } } } while (0)
; __device__ __forceinline__ void xcd_barrier(unsigned* bar, volatile LAS unsigned* st) {
;     ...
;       const unsigned og = xb_add(&bar[XB_TOP], 1u);
;       const unsigned tg = og / nx;
;       if (og + 1u == (tg + 1u) * nx) xb_add(&bar[XB_TOPGEN], 1u);
;       else XB_SPIN(xb_ld(&bar[XB_TOPGEN]) == tg, bar);
;       __builtin_amdgcn_fence(__ATOMIC_ACQUIRE, "agent");
;       xb_add(&bar[XB_XGEN(x)], 1u);
;       asm volatile("s_waitcnt vmcnt(0)" ::: "memory");
;     } else {
;       XB_SPIN(xb_ld(&bar[XB_XGEN(x)]) == gen, bar);
.Lbar6_8:
	v_mov_b32_e32 v0, 0x3000
	global_load_dword v0, v0, s[8:9] offset:1280 sc1
	s_add_u32 s4, s8, 0x3500
	s_addc_u32 s5, s9, 0
	s_waitcnt vmcnt(0)
	v_cmp_eq_u32_e32 vcc, v0, v1
	s_and_saveexec_b64 s[2:3], vcc
	s_cbranch_execz .LBB0_1300
	s_mov_b32 s23, 1
	s_mov_b64 s[12:13], 0
	v_mov_b32_e32 v0, 0
	s_branch .LBB0_1291

; __device__ __forceinline__ unsigned xb_ld(unsigned* p)              { return __hip_atomic_load(p, __ATOMIC_RELAXED, __HIP_MEMORY_SCOPE_AGENT); }
; __device__ __forceinline__ unsigned xb_add(unsigned* p, unsigned v) { return __hip_atomic_fetch_add(p, v, __ATOMIC_RELAXED, __HIP_MEMORY_SCOPE_AGENT); }
; #define XB_SPIN(cond, bar) do { unsigned _sp = 0; while (cond) { __builtin_amdgcn_s_sleep(1); \
;     if ((++_sp & 255u) == 0u) { if (xb_ld(&(bar)[XB_TMO])) break; if (_sp > XB_SPIN_CAP) { atomicAdd(&(bar)[XB_TMO], 1u); break; } } } } while (0)
; __device__ __forceinline__ void xcd_barrier(unsigned* bar, volatile LAS unsigned* st) {
;     ...
;       const unsigned og = xb_add(&bar[XB_TOP], 1u);
;       const unsigned tg = og / nx;
;       if (og + 1u == (tg + 1u) * nx) xb_add(&bar[XB_TOPGEN], 1u);
;       else XB_SPIN(xb_ld(&bar[XB_TOPGEN]) == tg, bar);
;       __builtin_amdgcn_fence(__ATOMIC_ACQUIRE, "agent");
;       xb_add(&bar[XB_XGEN(x)], 1u);
;       asm volatile("s_waitcnt vmcnt(0)" ::: "memory");
;     } else {
;       XB_SPIN(xb_ld(&bar[XB_XGEN(x)]) == gen, bar);
.Lbar6_25:
	v_mov_b32_e32 v0, 0x3000
	global_load_dword v0, v0, s[4:5] offset:1280 sc1
	s_add_u32 s10, s4, 0x3500
	s_addc_u32 s11, s5, 0
	s_waitcnt vmcnt(0)
	v_cmp_eq_u32_e32 vcc, v0, v1
	s_and_saveexec_b64 s[2:3], vcc
	s_cbranch_execz .LBB0_2731
	s_mov_b32 s22, 1
	s_mov_b64 s[12:13], 0
	v_mov_b32_e32 v0, 0
	s_branch .LBB0_2722
